# attention items: static s_setprio 1 on waves 0-3 only (opposite half, to pick the faster)
# baseline (speedup 1.0000x reference)
.LBB0_725:
	s_and_b32 s13, s7, 1
	s_and_b32 s12, s6, 3
	s_lshl_b32 s11, s13, 13
	s_and_b64 s[2:3], exec, s[4:5]
	s_cselect_b32 s2, s13, s8
	s_cselect_b32 s3, 0x4000, s11
	s_lshl_b32 s2, s2, 8
	s_or_b32 s14, s2, s3
	s_cmp_lt_i32 s9, 1
	s_mov_b64 s[6:7], -1
	s_cbranch_scc1 .LBB0_766
	s_cmp_lg_u32 s9, 1
	s_cbranch_scc0 .LBB0_751
	s_lshl_b32 s2, s12, 7
	s_load_dwordx2 s[34:35], s[0:1], 0xe0
	s_add_u32 s2, s68, s2
	v_readlane_b32 s6, v254, 50
	s_addc_u32 s3, s69, 0
	s_or_b32 s6, s12, s6
	s_ashr_i32 s7, s6, 31
	s_lshl_b64 s[6:7], s[6:7], 2
	s_waitcnt lgkmcnt(0)
	s_add_u32 s6, s34, s6
	s_addc_u32 s7, s35, s7
	s_waitcnt vmcnt(0)
	v_mov_b32_e32 v8, v156
	global_load_dword v9, v1, s[6:7]
	s_nop 0
	v_ashrrev_i32_e32 v4, 6, v8
	v_and_b32_e32 v6, 31, v8
	v_lshlrev_b32_e32 v7, 5, v4
	v_or_b32_e32 v0, s14, v6
	v_add_u32_e32 v128, v0, v7
	v_ashrrev_i32_e32 v129, 31, v128
	v_bfe_u32 v140, v8, 5, 1
	v_lshlrev_b64 v[2:3], 10, v[128:129]
	v_lshl_add_u64 v[2:3], s[2:3], 0, v[2:3]
	v_lshlrev_b32_e32 v0, 4, v140
	v_lshl_add_u64 v[2:3], v[2:3], 0, v[0:1]
	global_load_dwordx4 v[96:99], v[2:3], off
	global_load_dwordx4 v[100:103], v[2:3], off offset:32
	global_load_dwordx4 v[104:107], v[2:3], off offset:64
	global_load_dwordx4 v[108:111], v[2:3], off offset:96
	v_cmp_gt_i32_e32 vcc, 4, v4
	s_and_saveexec_b64 s[2:3], vcc
	s_cbranch_execz .Lprio_skip_1
	s_setprio 1

.LBB0_751:
	s_and_b64 vcc, exec, s[6:7]
	s_cbranch_vccz .LBB0_765
	s_waitcnt vmcnt(1)
	v_mov_b32_e32 v3, v156
	s_lshl_b32 s8, s12, 6
	v_and_b32_e32 v2, 31, v3
	s_waitcnt vmcnt(0)
	v_ashrrev_i32_e32 v6, 6, v3
	v_or_b32_e32 v0, s14, v2
	s_lshl_b32 s2, s12, 7
	v_lshl_add_u32 v128, v6, 5, v0
	s_add_u32 s2, s94, s2
	v_ashrrev_i32_e32 v129, 31, v128
	s_addc_u32 s3, s95, 0
	v_bfe_u32 v140, v3, 5, 1
	v_lshlrev_b64 v[4:5], 10, v[128:129]
	v_lshl_add_u64 v[4:5], s[2:3], 0, v[4:5]
	v_lshlrev_b32_e32 v0, 4, v140
	v_lshl_add_u64 v[4:5], v[4:5], 0, v[0:1]
	global_load_dwordx4 v[112:115], v[4:5], off
	global_load_dwordx4 v[108:111], v[4:5], off offset:32
	global_load_dwordx4 v[104:107], v[4:5], off offset:64
	global_load_dwordx4 v[100:103], v[4:5], off offset:96
	v_cmp_gt_i32_e32 vcc, 4, v6
	s_and_saveexec_b64 s[2:3], vcc
	s_cbranch_execz .Lprio_skip_2
	s_setprio 1

.LBB0_766:
	s_andn2_b64 vcc, exec, s[6:7]
	s_cbranch_vccnz .LBB0_790
	s_mul_i32 s2, s12, 0x60
	s_lshl_b32 s6, s2, 1
	s_waitcnt vmcnt(0)
	v_mov_b32_e32 v17, v156
	s_add_u32 s2, s86, s6
	s_addc_u32 s3, s87, 0
	v_and_b32_e32 v16, 31, v17
	v_ashrrev_i32_e32 v4, 6, v17
	v_or_b32_e32 v0, s14, v16
	v_bfe_u32 v140, v17, 5, 1
	v_lshl_add_u32 v128, v4, 5, v0
	v_mov_b64_e32 v[2:3], s[2:3]
	s_movk_i32 s2, 0x300
	v_mad_i64_i32 v[2:3], s[2:3], v128, s2, v[2:3]
	v_lshlrev_b32_e32 v0, 4, v140
	v_lshl_add_u64 v[2:3], v[2:3], 0, v[0:1]
	global_load_dwordx4 v[120:123], v[2:3], off
	global_load_dwordx4 v[116:119], v[2:3], off offset:32
	global_load_dwordx4 v[112:115], v[2:3], off offset:64
	global_load_dwordx4 v[108:111], v[2:3], off offset:96
	global_load_dwordx4 v[104:107], v[2:3], off offset:128
	global_load_dwordx4 v[100:103], v[2:3], off offset:160
	v_cmp_gt_i32_e32 vcc, 4, v4
	s_and_saveexec_b64 s[2:3], vcc
	s_cbranch_execz .Lprio_skip_3
	s_setprio 1
